# adds P3 job rebalancing (compress WGs skip token_prep, toks spread over remaining WGs) on top of previous: selmask cache, hand-written GDN scan ring, XCD-affine tile queues, top-k early exit, phase-C
# speedup vs baseline: 1.1997x; 1.0051x over previous
.LBB0_254:
	s_or_b64 exec, exec, s[36:37]
	v_readlane_b32 s36, v254, 0
	v_readlane_b32 s37, v254, 1
	s_mov_b32 s25, s82
	s_waitcnt lgkmcnt(0)
	s_barrier
	s_cmpk_gt_i32 s25, 0xa7f
	s_cbranch_scc1 .LBB0_424
	v_readlane_b32 s2, v255, 30
	s_mul_i32 s38, s2, 0xc0
	s_lshl_b32 s84, s2, 6
	s_lshl_b32 s94, s2, 2
	s_lshl_b32 s2, s25, 11
	s_add_i32 s92, s2, 0xffb00000
	s_lshl_b32 s2, s25, 6
	s_mov_b32 s39, s85
	s_add_i32 s93, s25, 0xfffff600
	s_add_i32 s91, s2, 0xfffd8000
	s_lshl_b64 s[88:89], s[84:85], 2
	s_mov_b32 s90, s25
	s_mov_b32 s32, s25
	v_readlane_b32 s3, v255, 31
	s_branch .LBB0_258

.LBB0_257:
	v_readlane_b32 s2, v254, 2
	s_nop 0
	s_add_i32 s32, s32, s2
	s_cmpk_gt_i32 s32, 0xaff
	s_cbranch_scc1 .LBB0_424
	s_mov_b32 s90, s32
	s_cmpk_lt_i32 s32, 0x800
	s_cbranch_scc1 .Lp3_mapped
	s_add_i32 s90, s32, 0x200
	s_cmpk_lt_i32 s32, 0x880
	s_cbranch_scc1 .Lp3_mapped
	s_add_i32 s90, s32, 0xffffff80
	s_cmpk_lt_i32 s32, 0xa00
	s_cbranch_scc1 .Lp3_mapped
	s_cmpk_lt_i32 s32, 0xa80
	s_cbranch_scc1 .LBB0_257
	s_add_i32 s90, s32, 0xffffff00
.Lp3_mapped:
	s_mov_b32 s25, s90
	s_add_i32 s93, s90, 0xfffff600
	s_lshl_b32 s92, s93, 11
	s_lshl_b32 s91, s93, 6
